# v1 plus padding: attention steady-loop head at 24 mod 64, later phases as v1 mod 64
# baseline (speedup 1.0000x reference)
; #define WAIT_BAR(N) asm volatile("s_waitcnt vmcnt(" #N ") lgkmcnt(0)\n\ts_barrier":::"memory")
;   #define DMA_K(t,slot) glds16(ksrc+(long)(t)*KVBLK*DM,(unsigned)__builtin_amdgcn_readfirstlane(kdst+(slot)))
;   #define DMA_V(t,slot) do{ glds16(vsrc+(long)(t)*KVBLK*DM,(unsigned)__builtin_amdgcn_readfirstlane(vdst+(slot))); glds16(vsrc+64+(long)(t)*KVBLK*DM,(unsigned)__builtin_amdgcn_readfirstlane(vdst2+(slot))); }while(0)
;   #define CMASK(P0,P1,t) do{int jb_=(t)-(NT-4); if(jb_>=0)cmask(P0,P1,jb_,qrel,hi);}while(0)
;   #define START(P0,P1) do{ resc=false; \
;     { _Pragma("unroll") for(int r=0;r<16;++r){P0[r]=fsub_s(P0[r],mhat);P1[r]=fsub_s(P1[r],mhat);} \
;       } \
;     _Pragma("unroll") for(int r=0;r<16;++r)P0[r]=__builtin_amdgcn_exp2f(P0[r]); }while(0)
;   #define ROT() do{sl_prev=sl_cur;sl_cur=sl_next;sl_next=(sl_next==(NSLOT-1)*SLOTB)?0:sl_next+SLOTB;}while(0)
;   #define CMASK(P0,P1,t) do{}while(0)
;   #define CMASK(P0,P1,t) do{int jb_=(t)-(NT-4); if(jb_>=0)cmask(P0,P1,jb_,qrel,hi);}while(0)
; template<int THRL> __device__ __forceinline__ void attn_unit(int b,int h,int qb,unsigned char*wsb,char*shm,float kmax,const int CMB,float lam){
;     ...
;   const float mhat=sqrtf(q2_)*kmax*1.004f+0.02f;
;   float l_reg=0.f;f32x16 o[2];o[0]=f32x16{};o[1]=f32x16{};f32x16 o2[2];o2[0]=f32x16{};o2[1]=f32x16{};const f32x16 negm=f32x16{};
;   const int qrel=wid*QBLK+r32;
;     ...
;   bool resc=false;
;     ...
;   f32x16 pA0,pA1,pB0,pB1;
;   int sl_prev=0,sl_cur=0,sl_next=SLOTB;
;     ...
;   DMA_K(2,2*SLOTB);
;   WAIT_BAR(4);
;   qkt(pA0,pA1,Kbase,qr,negm,r32,hi);asm volatile("s_nop 15\n\ts_nop 7":"+v"(pA0),"+v"(pA1));CMASK(pA0,pA1,0);
;   START(pA0,pA1);
;   _Pragma("unroll") for(int r=0;r<16;++r)pA1[r]=__builtin_amdgcn_exp2f(pA1[r]);
;   WAIT_BAR(0);
;   DMA_K(3,0);DMA_V(1,SLOTB);
;   ROT();
;   kload8(kf,kp0+sl_cur);
;   WAIT_BAR(3);
.LBB0_309:
	v_mov_b32_e32 v39, s6
	v_add_f32_e32 v39, s5, v39
	v_mul_f32_e32 v40, 0x4f800000, v39
	v_cmp_gt_f32_e32 vcc, s74, v39
	v_add_f32_e32 v37, v37, v38
	v_mul_f32_e32 v38, 0x4f800000, v37
	v_cndmask_b32_e32 v39, v39, v40, vcc
	v_sqrt_f32_e32 v40, v39
	s_waitcnt vmcnt(0) lgkmcnt(0)
	s_barrier
	s_cmp_lg_u32 0, -1
	s_mov_b32 s37, 0
	v_add_u32_e32 v41, -1, v40
	v_fma_f32 v42, -v41, v40, v39
	v_cmp_ge_f32_e64 s[4:5], 0, v42
	v_add_u32_e32 v42, 1, v40
	s_mov_b32 s6, 1
	v_cndmask_b32_e64 v41, v40, v41, s[4:5]
	v_fma_f32 v40, -v42, v40, v39
	v_cmp_lt_f32_e64 s[4:5], 0, v40
	s_nop 1
	v_cndmask_b32_e64 v40, v41, v42, s[4:5]
	v_mul_f32_e32 v41, 0x37800000, v40
	v_cndmask_b32_e32 v40, v40, v41, vcc
	v_cmp_class_f32_e32 vcc, v39, v237
	s_nop 1
	v_cndmask_b32_e32 v39, v40, v39, vcc
	v_cmp_gt_f32_e32 vcc, s74, v37
	v_lshlrev_b32_e32 v40, 1, v36
	v_and_b32_e32 v251, 32, v40
	v_cndmask_b32_e32 v37, v37, v38, vcc
	v_sqrt_f32_e32 v38, v37
	v_lshlrev_b32_e32 v40, 4, v36
	v_and_b32_e32 v40, 0xc0, v40
	v_lshl_or_b32 v246, v242, 8, v40
	v_add_u32_e32 v40, 0, v251
	v_add3_u32 v252, v40, v249, v246
	v_add_u32_e32 v40, -1, v38
	v_fma_f32 v41, -v40, v38, v37
	v_cmp_ge_f32_e64 s[4:5], 0, v41
	v_add_u32_e32 v41, 1, v38
	v_mul_f32_e32 v39, 0x3f8147ae, v39
	v_cndmask_b32_e64 v40, v38, v40, s[4:5]
	v_fma_f32 v38, -v41, v38, v37
	v_cmp_lt_f32_e64 s[4:5], 0, v38
	s_nop 1
	v_cndmask_b32_e64 v38, v40, v41, s[4:5]
	v_mul_f32_e32 v40, 0x37800000, v38
	v_cndmask_b32_e32 v38, v38, v40, vcc
	v_cmp_class_f32_e32 vcc, v37, v237
	s_mov_b64 s[4:5], 0x60000
	s_nop 0
	v_cndmask_b32_e32 v37, v38, v37, vcc
	v_mul_f32_e32 v37, v39, v37
	v_fmamk_f32 v247, v37, 0x3f808312, v238
	v_sub_f32_e32 v0, v0, v247
	v_sub_f32_e32 v1, v1, v247
	v_sub_f32_e32 v16, v16, v247
	v_sub_f32_e32 v17, v17, v247
	v_sub_f32_e32 v2, v2, v247
	v_sub_f32_e32 v18, v18, v247
	s_nop 0
	v_exp_f32_e32 v96, v0
	v_exp_f32_e32 v97, v1
	v_lshl_add_u64 v[0:1], v[32:33], 0, s[4:5]
	s_mov_b32 s4, m0
	s_mov_b32 m0, s3
	s_nop 0
	global_load_lds_dwordx4 v[0:1], off
	s_mov_b32 m0, s4
	s_mov_b64 s[4:5], 0x20000
	v_lshl_add_u64 v[0:1], v[34:35], 0, s[4:5]
	s_cselect_b32 s4, 0, 0
	s_add_i32 s1, s4, s1
	s_add_i32 s4, s1, 0x8000
	s_mov_b32 s5, m0
	s_mov_b32 m0, s4
	s_nop 0
	global_load_lds_dwordx4 v[0:1], off
	s_mov_b32 m0, s5
	s_mov_b64 s[4:5], 0x20080
	v_lshl_add_u64 v[0:1], v[34:35], 0, s[4:5]
	s_add_i32 s1, s1, 0xe000
	s_mov_b32 s4, m0
	s_mov_b32 m0, s1
	s_nop 0
	global_load_lds_dwordx4 v[0:1], off
	s_mov_b32 m0, s4
	ds_read_b128 v[204:207], v250 offset:8192
	ds_read_b128 v[200:203], v250 offset:8704
	ds_read_b128 v[196:199], v250 offset:10240
	ds_read_b128 v[192:195], v250 offset:10752
	ds_read_b128 v[188:191], v250 offset:12288
	ds_read_b128 v[184:187], v250 offset:12800
	ds_read_b128 v[180:183], v250 offset:14336
	ds_read_b128 v[176:179], v250 offset:14848
	v_sub_f32_e32 v3, v3, v247
	v_sub_f32_e32 v19, v19, v247
	v_sub_f32_e32 v4, v4, v247
	v_sub_f32_e32 v20, v20, v247
	v_sub_f32_e32 v5, v5, v247
	v_sub_f32_e32 v21, v21, v247
	v_sub_f32_e32 v6, v6, v247
	v_sub_f32_e32 v22, v22, v247
	v_sub_f32_e32 v7, v7, v247
	v_sub_f32_e32 v23, v23, v247
	v_sub_f32_e32 v8, v8, v247
	v_sub_f32_e32 v24, v24, v247
	v_sub_f32_e32 v9, v9, v247
	v_sub_f32_e32 v25, v25, v247
	v_sub_f32_e32 v10, v10, v247
	v_sub_f32_e32 v26, v26, v247
	v_sub_f32_e32 v11, v11, v247
	v_sub_f32_e32 v27, v27, v247
	v_sub_f32_e32 v12, v12, v247
	v_sub_f32_e32 v28, v28, v247
	v_sub_f32_e32 v13, v13, v247
	v_sub_f32_e32 v29, v29, v247
	v_sub_f32_e32 v14, v14, v247
	v_sub_f32_e32 v30, v30, v247
	v_sub_f32_e32 v15, v15, v247
	v_sub_f32_e32 v31, v31, v247
	v_exp_f32_e32 v98, v2
	v_exp_f32_e32 v99, v3
	v_exp_f32_e32 v100, v4
	v_exp_f32_e32 v101, v5
	v_exp_f32_e32 v102, v6
	v_exp_f32_e32 v103, v7
	v_exp_f32_e32 v104, v8
	v_exp_f32_e32 v105, v9
	v_exp_f32_e32 v106, v10
	v_exp_f32_e32 v107, v11
	v_exp_f32_e32 v108, v12
	v_exp_f32_e32 v109, v13
	v_exp_f32_e32 v110, v14
	v_exp_f32_e32 v111, v15
	v_exp_f32_e32 v80, v16
	v_exp_f32_e32 v81, v17
	v_exp_f32_e32 v82, v18
	v_exp_f32_e32 v83, v19
	v_exp_f32_e32 v84, v20
	v_exp_f32_e32 v85, v21
	v_exp_f32_e32 v86, v22
	v_exp_f32_e32 v87, v23
	v_exp_f32_e32 v88, v24
	v_exp_f32_e32 v89, v25
	v_exp_f32_e32 v90, v26
	v_exp_f32_e32 v91, v27
	v_exp_f32_e32 v92, v28
	v_exp_f32_e32 v93, v29
	v_exp_f32_e32 v94, v30
	v_exp_f32_e32 v95, v31
	s_waitcnt vmcnt(3) lgkmcnt(0)
	s_barrier
	v_and_b32_e32 v0, 3, v36
	s_andn2_b64 vcc, exec, s[54:55]
	v_lshlrev_b32_e32 v208, 4, v0
	s_cbranch_vccnz .LBB0_313
; template<int THRL> __device__ __forceinline__ void attn_unit(int b,int h,int qb,unsigned char*wsb,char*shm,float kmax,const int CMB,float lam){
;     ...
;   float l_reg=0.f;f32x16 o[2];o[0]=f32x16{};o[1]=f32x16{};f32x16 o2[2];o2[0]=f32x16{};o2[1]=f32x16{};const f32x16 negm=f32x16{};
;   const int qrel=wid*QBLK+r32;
;     ...
;   bool resc=false;
;     ...
;   f32x16 pA0,pA1,pB0,pB1;
;   int sl_prev=0,sl_cur=0,sl_next=SLOTB;
	s_lshl_b32 s1, s43, 6
	s_add_i32 s6, s79, s1
	s_lshr_b32 s4, s6, 7
	s_mov_b32 s5, s7
	s_lshl_b64 s[4:5], s[4:5], 8
	s_lshl_b64 s[36:37], s[68:69], 1
	s_add_u32 s4, s36, s4
	v_mov_b32_e32 v209, v221
	s_addc_u32 s5, s37, s5
	s_lshl_b32 s1, s95, 9
	v_lshl_add_u64 v[0:1], s[4:5], 0, v[208:209]
	s_and_b32 s1, s1, 0x18000
	s_lshl_b64 s[4:5], s[66:67], 1
	s_lshl_b64 s[36:37], s[6:7], 1
	v_lshl_or_b32 v2, v214, 11, s1
	s_add_u32 s1, s64, s36
	s_addc_u32 s6, s65, s37
	v_mov_b32_e32 v3, v221
	s_add_u32 s4, s1, s4
	v_lshl_add_u64 v[0:1], v[0:1], 0, v[2:3]
	s_addc_u32 s5, s6, s5
	v_mov_b32_e32 v64, 0
	s_mov_b32 s33, 6
	v_lshl_add_u64 v[210:211], s[64:65], 0, v[0:1]
	v_lshl_add_u64 v[212:213], s[4:5], 0, v[220:221]
	s_movk_i32 s36, 0x4000
	s_movk_i32 s42, 0x2000
	s_mov_b32 s5, 0
	v_mov_b32_e32 v0, 0
	v_mov_b32_e32 v1, v64
	v_mov_b32_e32 v2, v64
	v_mov_b32_e32 v3, v64
	v_mov_b32_e32 v4, v64
	v_mov_b32_e32 v5, v64
	v_mov_b32_e32 v6, v64
	v_mov_b32_e32 v7, v64
	v_mov_b32_e32 v8, v64
	v_mov_b32_e32 v9, v64
	v_mov_b32_e32 v10, v64
	v_mov_b32_e32 v11, v64
	v_mov_b32_e32 v12, v64
	v_mov_b32_e32 v13, v64
	v_mov_b32_e32 v14, v64
	v_mov_b32_e32 v15, v64
	v_mov_b32_e32 v16, 0
	v_mov_b32_e32 v17, v64
	v_mov_b32_e32 v18, v64
	v_mov_b32_e32 v19, v64
	v_mov_b32_e32 v20, v64
	v_mov_b32_e32 v21, v64
	v_mov_b32_e32 v22, v64
	v_mov_b32_e32 v23, v64
	v_mov_b32_e32 v24, v64
	v_mov_b32_e32 v25, v64
	v_mov_b32_e32 v26, v64
	v_mov_b32_e32 v27, v64
	v_mov_b32_e32 v28, v64
	v_mov_b32_e32 v29, v64
	v_mov_b32_e32 v30, v64
	v_mov_b32_e32 v31, v64
	v_mov_b32_e32 v32, 0
	v_mov_b32_e32 v33, v64
	v_mov_b32_e32 v34, v64
	v_mov_b32_e32 v35, v64
	v_mov_b32_e32 v36, v64
	v_mov_b32_e32 v37, v64
	v_mov_b32_e32 v38, v64
	v_mov_b32_e32 v39, v64
	v_mov_b32_e32 v40, v64
	v_mov_b32_e32 v41, v64
	v_mov_b32_e32 v42, v64
	v_mov_b32_e32 v43, v64
	v_mov_b32_e32 v44, v64
	v_mov_b32_e32 v45, v64
	v_mov_b32_e32 v46, v64
	v_mov_b32_e32 v47, v64
	v_mov_b32_e32 v48, 0
	v_mov_b32_e32 v49, v64
	v_mov_b32_e32 v50, v64
	v_mov_b32_e32 v51, v64
	v_mov_b32_e32 v52, v64
	v_mov_b32_e32 v53, v64
	v_mov_b32_e32 v54, v64
	v_mov_b32_e32 v55, v64
	v_mov_b32_e32 v56, v64
	v_mov_b32_e32 v57, v64
	v_mov_b32_e32 v58, v64
	v_mov_b32_e32 v59, v64
	v_mov_b32_e32 v60, v64
	v_mov_b32_e32 v61, v64
	v_mov_b32_e32 v62, v64
	v_mov_b32_e32 v63, v64
	v_lshlrev_b32_e32 v143, 2, v230
	v_add_u32_e32 v143, 0x12800, v143
	ds_write_b32 v143, v246 offset:32768
	ds_write_b32 v143, v230
	ds_write_b32 v143, v231 offset:2048
	ds_write_b32 v143, v232 offset:4096
	ds_write_b32 v143, v233 offset:6144
	ds_write_b32 v143, v234 offset:8192
	ds_write_b32 v143, v235 offset:10240
	ds_write_b32 v143, v236 offset:12288
	ds_write_b32 v143, v237 offset:14336
	ds_write_b32 v143, v238 offset:16384
	ds_write_b32 v143, v239 offset:18432
	ds_write_b32 v143, v240 offset:20480
	ds_write_b32 v143, v241 offset:22528
	ds_write_b32 v143, v242 offset:24576
	ds_write_b32 v143, v243 offset:26624
	ds_write_b32 v143, v244 offset:28672
	ds_write_b32 v143, v245 offset:30720
	v_mov_b32_e32 v246, v143
	v_xor_b32_e32 v230, 0x80000000, v247
	v_mov_b32_e32 v231, v230
	v_mov_b32_e32 v232, v230
	v_mov_b32_e32 v233, v230
	v_mov_b32_e32 v234, v230
	v_mov_b32_e32 v235, v230
	v_mov_b32_e32 v236, v230
	v_mov_b32_e32 v237, v230
	v_mov_b32_e32 v238, v230
	v_mov_b32_e32 v239, v230
	v_mov_b32_e32 v240, v230
	v_mov_b32_e32 v241, v230
	v_mov_b32_e32 v242, v230
	v_mov_b32_e32 v243, v230
	v_mov_b32_e32 v244, v230
	v_mov_b32_e32 v245, v230
	s_waitcnt lgkmcnt(0)
	s_nop 0
	s_nop 0
	s_nop 0
	s_nop 0
	s_nop 0
	s_nop 0
	s_nop 0
	s_nop 0
	s_nop 0
	s_nop 0
	s_nop 0
	s_nop 0
.LBB0_311:
	s_mov_b32 s37, s36
	s_mov_b32 s4, s33
	s_mov_b32 s1, s42
	v_add_u32_e32 v209, s5, v252
	ds_read_b64_tr_b16 v[216:217], v209 offset:24576
	ds_read_b64_tr_b16 v[218:219], v209 offset:25088
	v_add_f32_e32 v65, v96, v97
	v_add_f32_e32 v65, v98, v65
	v_add_f32_e32 v65, v99, v65
	v_add_f32_e32 v65, v100, v65
	v_add_f32_e32 v65, v101, v65
	v_cvt_pk_bf16_f32 v172, v96, v97
	v_cvt_pk_bf16_f32 v173, v98, v99
	s_waitcnt lgkmcnt(9)
	v_mfma_f32_32x32x16_bf16 v[128:143], v[204:207], v[156:159], v[230:245]
	ds_read_b64_tr_b16 v[204:205], v209 offset:28672
	ds_read_b64_tr_b16 v[206:207], v209 offset:29184
	v_add_f32_e32 v65, v102, v65
	v_add_f32_e32 v65, v103, v65
	v_add_f32_e32 v65, v104, v65
	v_add_f32_e32 v65, v105, v65
	v_cvt_pk_bf16_f32 v174, v100, v101
	v_cvt_pk_bf16_f32 v175, v102, v103
	s_waitcnt lgkmcnt(10)
	v_mfma_f32_32x32x16_bf16 v[112:127], v[200:203], v[156:159], v[230:245]
	ds_read_b64_tr_b16 v[74:75], v209 offset:25600
	ds_read_b64_tr_b16 v[76:77], v209 offset:26112
	v_add_f32_e32 v65, v106, v65
	v_add_f32_e32 v65, v107, v65
	v_add_f32_e32 v65, v108, v65
	v_add_f32_e32 v65, v109, v65
	v_cvt_pk_bf16_f32 v168, v104, v105
	v_cvt_pk_bf16_f32 v169, v106, v107
	s_waitcnt lgkmcnt(11)
	v_mfma_f32_32x32x16_bf16 v[128:143], v[196:199], v[152:155], v[128:143]
	ds_read_b64_tr_b16 v[70:71], v209 offset:29696
	ds_read_b64_tr_b16 v[72:73], v209 offset:30208
	v_add_f32_e32 v65, v110, v65
	v_add_f32_e32 v65, v111, v65
	v_add_f32_e32 v65, v80, v65
	v_add_f32_e32 v65, v81, v65
	v_cvt_pk_bf16_f32 v170, v108, v109
	v_cvt_pk_bf16_f32 v171, v110, v111
	s_waitcnt lgkmcnt(12)
	v_mfma_f32_32x32x16_bf16 v[112:127], v[192:195], v[152:155], v[112:127]
	ds_read_b64_tr_b16 v[66:67], v209 offset:26624
	ds_read_b64_tr_b16 v[68:69], v209 offset:27136
	v_add_f32_e32 v65, v82, v65
	v_add_f32_e32 v65, v83, v65
	v_add_f32_e32 v65, v84, v65
	v_add_f32_e32 v65, v85, v65
	v_cvt_pk_bf16_f32 v164, v80, v81
	v_cvt_pk_bf16_f32 v165, v82, v83
	s_waitcnt lgkmcnt(13)
	v_mfma_f32_32x32x16_bf16 v[128:143], v[188:191], v[148:151], v[128:143]
	ds_read_b64_tr_b16 v[100:101], v209 offset:30720
	ds_read_b64_tr_b16 v[102:103], v209 offset:31232
	v_add_f32_e32 v65, v86, v65
	v_add_f32_e32 v65, v87, v65
	v_add_f32_e32 v65, v88, v65
	v_add_f32_e32 v65, v89, v65
	v_cvt_pk_bf16_f32 v166, v84, v85
	v_cvt_pk_bf16_f32 v167, v86, v87
	s_waitcnt lgkmcnt(14)
	v_mfma_f32_32x32x16_bf16 v[112:127], v[184:187], v[148:151], v[112:127]
	ds_read_b64_tr_b16 v[96:97], v209 offset:27648
	ds_read_b64_tr_b16 v[98:99], v209 offset:28160
	v_add_f32_e32 v65, v90, v65
	v_add_f32_e32 v65, v91, v65
	v_add_f32_e32 v65, v92, v65
	v_add_f32_e32 v65, v93, v65
	v_cvt_pk_bf16_f32 v160, v88, v89
	v_cvt_pk_bf16_f32 v161, v90, v91
	s_waitcnt lgkmcnt(14)
	v_mfma_f32_32x32x16_bf16 v[128:143], v[180:183], v[144:147], v[128:143]
	ds_read_b64_tr_b16 v[86:87], v209 offset:31744
	ds_read_b64_tr_b16 v[88:89], v209 offset:32256
	v_add_f32_e32 v65, v94, v65
	v_add_f32_e32 v65, v95, v65
	v_add_f32_e32 v65, 0, v65
	v_cvt_pk_bf16_f32 v162, v92, v93
	v_cvt_pk_bf16_f32 v163, v94, v95
	v_mfma_f32_32x32x16_bf16 v[112:127], v[176:179], v[144:147], v[112:127]
	v_lshl_add_u64 v[190:191], v[212:213], 0, s[48:49]
	v_lshl_add_u64 v[78:79], v[190:191], 0, s[10:11]
	s_add_i32 s5, s42, s3
	s_mov_b32 s6, m0
	s_mov_b32 m0, s5
	s_nop 0
	global_load_lds_dwordx4 v[78:79], off
	s_mov_b32 m0, s6
	v_lshl_add_u64 v[188:189], v[210:211], 0, s[48:49]
	v_lshl_add_u64 v[78:79], v[188:189], 0, s[12:13]
	s_add_i32 s5, s36, s97
	s_mov_b32 s6, m0
	s_mov_b32 m0, s5
	s_nop 0
	global_load_lds_dwordx4 v[78:79], off
	s_mov_b32 m0, s6
	v_lshl_add_u64 v[78:79], v[188:189], 0, s[14:15]
	s_add_i32 s5, s36, s96
	s_mov_b32 s6, m0
	s_mov_b32 m0, s5
	s_nop 0
	global_load_lds_dwordx4 v[78:79], off
	s_mov_b32 m0, s6
	s_waitcnt lgkmcnt(14)
	v_mfma_f32_32x32x16_bf16 v[32:47], v[172:175], v[216:219], v[32:47]
	v_exp_f32_e32 v128, v128
	v_exp_f32_e32 v129, v129
	ds_read_b64_tr_b16 v[90:91], v209 offset:49152
	ds_read_b64_tr_b16 v[92:93], v209 offset:49664
	s_waitcnt lgkmcnt(14)
	v_mfma_f32_32x32x16_bf16 v[48:63], v[172:175], v[204:207], v[48:63]
	v_exp_f32_e32 v130, v130
	v_exp_f32_e32 v131, v131
	ds_read_b64_tr_b16 v[104:105], v209 offset:53248
	ds_read_b64_tr_b16 v[106:107], v209 offset:53760
	v_add_u32_e32 v94, s37, v250
	ds_read_b128 v[82:85], v94
	ds_read_b128 v[78:81], v94 offset:512
	s_waitcnt lgkmcnt(14)
	v_mfma_f32_32x32x16_bf16 v[32:47], v[168:171], v[74:77], v[32:47]
	v_exp_f32_e32 v132, v132
	v_exp_f32_e32 v133, v133
	ds_read_b64_tr_b16 v[108:109], v209 offset:50176
	ds_read_b64_tr_b16 v[110:111], v209 offset:50688
	ds_read_b128 v[184:187], v94 offset:2048
	ds_read_b128 v[176:179], v94 offset:2560
	v_mfma_f32_32x32x16_bf16 v[48:63], v[168:171], v[70:73], v[48:63]
	v_exp_f32_e32 v134, v134
	v_exp_f32_e32 v135, v135
	ds_read_b64_tr_b16 v[192:193], v209 offset:54272
	ds_read_b64_tr_b16 v[194:195], v209 offset:54784
	ds_read_b128 v[180:183], v94 offset:4096
	ds_read_b128 v[70:73], v94 offset:4608
	s_waitcnt lgkmcnt(14)
	v_mfma_f32_32x32x16_bf16 v[32:47], v[164:167], v[66:69], v[32:47]
	v_exp_f32_e32 v136, v136
	v_exp_f32_e32 v137, v137
	ds_read_b64_tr_b16 v[196:197], v209 offset:51200
	ds_read_b64_tr_b16 v[198:199], v209 offset:51712
	ds_read_b128 v[74:77], v94 offset:6144
	ds_read_b128 v[66:69], v94 offset:6656
	v_mfma_f32_32x32x16_bf16 v[48:63], v[164:167], v[100:103], v[48:63]
	v_exp_f32_e32 v138, v138
	v_exp_f32_e32 v139, v139
	ds_read_b64_tr_b16 v[100:101], v209 offset:55296
	ds_read_b64_tr_b16 v[102:103], v209 offset:55808
	v_mfma_f32_32x32x16_bf16 v[32:47], v[160:163], v[96:99], v[32:47]
	v_exp_f32_e32 v140, v140
	v_exp_f32_e32 v141, v141
	ds_read_b64_tr_b16 v[94:95], v209 offset:52224
	ds_read_b64_tr_b16 v[96:97], v209 offset:52736
	v_mfma_f32_32x32x16_bf16 v[48:63], v[160:163], v[86:89], v[48:63]
	v_exp_f32_e32 v142, v142
	v_exp_f32_e32 v143, v143
	ds_read_b64_tr_b16 v[86:87], v209 offset:56320
	ds_read_b64_tr_b16 v[88:89], v209 offset:56832
	s_waitcnt lgkmcnt(14)
	v_mfma_f32_32x32x16_bf16 v[0:15], v[172:175], v[90:93], v[0:15]
	v_exp_f32_e32 v112, v112
	v_exp_f32_e32 v113, v113
	v_mfma_f32_32x32x16_bf16 v[16:31], v[172:175], v[104:107], v[16:31]
	v_exp_f32_e32 v114, v114
	v_exp_f32_e32 v115, v115
	v_mfma_f32_32x32x16_bf16 v[0:15], v[168:171], v[108:111], v[0:15]
	v_exp_f32_e32 v116, v116
	v_exp_f32_e32 v117, v117
	s_waitcnt lgkmcnt(12)
	v_mfma_f32_32x32x16_bf16 v[16:31], v[168:171], v[192:195], v[16:31]
	v_exp_f32_e32 v118, v118
	v_exp_f32_e32 v119, v119
	s_waitcnt lgkmcnt(8)
	v_mfma_f32_32x32x16_bf16 v[0:15], v[164:167], v[196:199], v[0:15]
	v_exp_f32_e32 v120, v120
	v_exp_f32_e32 v121, v121
	s_waitcnt lgkmcnt(4)
	v_mfma_f32_32x32x16_bf16 v[16:31], v[164:167], v[100:103], v[16:31]
	v_exp_f32_e32 v122, v122
	v_exp_f32_e32 v123, v123
	s_waitcnt lgkmcnt(2)
	v_mfma_f32_32x32x16_bf16 v[0:15], v[160:163], v[94:97], v[0:15]
	v_exp_f32_e32 v124, v124
	v_exp_f32_e32 v125, v125
	s_waitcnt lgkmcnt(0)
	v_mfma_f32_32x32x16_bf16 v[16:31], v[160:163], v[86:89], v[16:31]
	v_exp_f32_e32 v126, v126
	v_exp_f32_e32 v127, v127
	s_waitcnt vmcnt(3) lgkmcnt(0)
	s_barrier
; #define WAIT_BAR(N) asm volatile("s_waitcnt vmcnt(" #N ") lgkmcnt(0)\n\ts_barrier":::"memory")
;   #define RESC() do{ if(resc){ asm volatile("s_waitcnt lgkmcnt(0)":::"memory"); \
;       _Pragma("unroll") for(int d_=0;d_<2;++d_) _Pragma("unroll") for(int r=0;r<16;++r){const float f_=wsf[crow(r,hi)];o[d_][r]*=f_;o2[d_][r]*=f_;} } }while(0)
;   #define ROT() do{sl_prev=sl_cur;sl_cur=sl_next;sl_next=(sl_next==(NSLOT-1)*SLOTB)?0:sl_next+SLOTB;}while(0)
; template<int THRL> __device__ __forceinline__ void attn_unit(int b,int h,int qb,unsigned char*wsb,char*shm,float kmax,const int CMB,float lam){
;     ...
;   int t=1;
;     ...
;   for(;t+5<NT;t+=2){
;     STEP(pB0,pB1,pA0,pA1,t,true,true,true);     WAIT_BAR(3); RESC(); ROT();
;     STEP(pA0,pA1,pB0,pB1,t+1,true,true,true);   WAIT_BAR(3); RESC(); ROT();
	s_add_i32 s5, s36, 0x2000
	s_cmpk_lg_i32 s36, 0x4000
	s_cselect_b32 s42, s5, 0
	v_add_u32_e32 v209, s1, v252
	ds_read_b64_tr_b16 v[192:193], v209 offset:24576
	ds_read_b64_tr_b16 v[194:195], v209 offset:25088
	v_mfma_f32_32x32x16_bf16 v[96:111], v[82:85], v[156:159], v[230:245]
	v_add_f32_e32 v86, v128, v129
	v_add_f32_e32 v86, v130, v86
	v_add_f32_e32 v86, v131, v86
	v_add_f32_e32 v86, v132, v86
	v_add_f32_e32 v86, v133, v86
	v_cvt_pk_bf16_f32 v172, v128, v129
	v_cvt_pk_bf16_f32 v173, v130, v131
	ds_read_b64_tr_b16 v[196:197], v209 offset:28672
	ds_read_b64_tr_b16 v[198:199], v209 offset:29184
	v_add_f32_e32 v82, v134, v86
	v_add_f32_e32 v82, v135, v82
	v_add_f32_e32 v82, v136, v82
	v_add_f32_e32 v128, v137, v82
	v_mfma_f32_32x32x16_bf16 v[80:95], v[78:81], v[156:159], v[230:245]
	v_cvt_pk_bf16_f32 v174, v132, v133
	v_cvt_pk_bf16_f32 v175, v134, v135
	ds_read_b64_tr_b16 v[216:217], v209 offset:25600
	ds_read_b64_tr_b16 v[218:219], v209 offset:26112
	v_mfma_f32_32x32x16_bf16 v[96:111], v[184:187], v[152:155], v[96:111]
	v_add_f32_e32 v78, v138, v128
	v_add_f32_e32 v78, v139, v78
	v_add_f32_e32 v78, v140, v78
	v_add_f32_e32 v78, v141, v78
	v_cvt_pk_bf16_f32 v168, v136, v137
	v_cvt_pk_bf16_f32 v169, v138, v139
	ds_read_b64_tr_b16 v[136:137], v209 offset:29696
	ds_read_b64_tr_b16 v[138:139], v209 offset:30208
	v_mfma_f32_32x32x16_bf16 v[80:95], v[176:179], v[152:155], v[80:95]
	v_add_f32_e32 v78, v142, v78
	v_add_f32_e32 v78, v143, v78
	v_add_f32_e32 v78, v112, v78
	v_add_f32_e32 v78, v113, v78
	v_cvt_pk_bf16_f32 v170, v140, v141
	v_cvt_pk_bf16_f32 v171, v142, v143
	ds_read_b64_tr_b16 v[132:133], v209 offset:26624
	ds_read_b64_tr_b16 v[134:135], v209 offset:27136
	v_mfma_f32_32x32x16_bf16 v[96:111], v[180:183], v[148:151], v[96:111]
	v_add_f32_e32 v78, v114, v78
	v_add_f32_e32 v78, v115, v78
	v_add_f32_e32 v78, v116, v78
	v_add_f32_e32 v78, v117, v78
	v_cvt_pk_bf16_f32 v164, v112, v113
	v_cvt_pk_bf16_f32 v165, v114, v115
	ds_read_b64_tr_b16 v[128:129], v209 offset:30720
	ds_read_b64_tr_b16 v[130:131], v209 offset:31232
	v_mfma_f32_32x32x16_bf16 v[80:95], v[70:73], v[148:151], v[80:95]
	v_add_f32_e32 v78, v118, v78
	v_add_f32_e32 v78, v119, v78
	v_add_f32_e32 v78, v120, v78
	v_add_f32_e32 v78, v121, v78
	v_cvt_pk_bf16_f32 v166, v116, v117
	v_cvt_pk_bf16_f32 v167, v118, v119
	ds_read_b64_tr_b16 v[112:113], v209 offset:27648
	ds_read_b64_tr_b16 v[114:115], v209 offset:28160
	v_mfma_f32_32x32x16_bf16 v[96:111], v[74:77], v[144:147], v[96:111]
	v_add_f32_e32 v70, v122, v78
	v_add_f32_e32 v70, v123, v70
	v_add_f32_e32 v70, v124, v70
	v_add_f32_e32 v78, v125, v70
	v_cvt_pk_bf16_f32 v160, v120, v121
	v_cvt_pk_bf16_f32 v161, v122, v123
	ds_read_b64_tr_b16 v[70:71], v209 offset:31744
	ds_read_b64_tr_b16 v[72:73], v209 offset:32256
	v_mfma_f32_32x32x16_bf16 v[80:95], v[66:69], v[144:147], v[80:95]
	v_add_f32_e32 v74, v126, v78
	v_add_f32_e32 v74, v127, v74
	v_add_f32_e32 v74, 0, v74
	v_cvt_pk_bf16_f32 v162, v124, v125
	v_cvt_pk_bf16_f32 v163, v126, v127
	v_lshl_add_u64 v[66:67], v[190:191], 0, s[16:17]
	s_add_i32 s1, s36, s3
	s_mov_b32 s5, m0
	s_mov_b32 m0, s1
	s_nop 0
	global_load_lds_dwordx4 v[66:67], off
	s_mov_b32 m0, s5
	v_lshl_add_u64 v[66:67], v[188:189], 0, s[18:19]
	s_add_i32 s1, s42, s97
	s_mov_b32 s5, m0
	s_mov_b32 m0, s1
	s_nop 0
	global_load_lds_dwordx4 v[66:67], off
	s_mov_b32 m0, s5
	v_lshl_add_u64 v[66:67], v[188:189], 0, s[20:21]
	s_add_i32 s1, s42, s96
	s_mov_b32 s5, m0
	s_mov_b32 m0, s1
	s_nop 0
	global_load_lds_dwordx4 v[66:67], off
	s_mov_b32 m0, s5
	s_waitcnt lgkmcnt(14)
	v_mfma_f32_32x32x16_bf16 v[32:47], v[172:175], v[192:195], v[32:47]
	v_exp_f32_e32 v96, v96
	v_exp_f32_e32 v97, v97
	ds_read_b64_tr_b16 v[66:67], v209 offset:49152
	ds_read_b64_tr_b16 v[68:69], v209 offset:49664
	s_waitcnt lgkmcnt(14)
	v_mfma_f32_32x32x16_bf16 v[48:63], v[172:175], v[196:199], v[48:63]
	v_exp_f32_e32 v98, v98
	v_exp_f32_e32 v99, v99
	ds_read_b64_tr_b16 v[76:77], v209 offset:53248
	ds_read_b64_tr_b16 v[78:79], v209 offset:53760
	v_add_u32_e32 v75, s42, v250
	ds_read_b128 v[204:207], v75
	ds_read_b128 v[200:203], v75 offset:512
	s_waitcnt lgkmcnt(14)
	v_mfma_f32_32x32x16_bf16 v[32:47], v[168:171], v[216:219], v[32:47]
	v_exp_f32_e32 v100, v100
	v_exp_f32_e32 v101, v101
	ds_read_b64_tr_b16 v[116:117], v209 offset:50176
	ds_read_b64_tr_b16 v[118:119], v209 offset:50688
	ds_read_b128 v[196:199], v75 offset:2048
	ds_read_b128 v[192:195], v75 offset:2560
	v_mfma_f32_32x32x16_bf16 v[48:63], v[168:171], v[136:139], v[48:63]
	v_exp_f32_e32 v102, v102
	v_exp_f32_e32 v103, v103
	ds_read_b64_tr_b16 v[120:121], v209 offset:54272
	ds_read_b64_tr_b16 v[122:123], v209 offset:54784
	ds_read_b128 v[188:191], v75 offset:4096
	ds_read_b128 v[184:187], v75 offset:4608
	s_waitcnt lgkmcnt(14)
	v_mfma_f32_32x32x16_bf16 v[32:47], v[164:167], v[132:135], v[32:47]
	v_exp_f32_e32 v104, v104
	v_exp_f32_e32 v105, v105
	ds_read_b64_tr_b16 v[124:125], v209 offset:51200
	ds_read_b64_tr_b16 v[126:127], v209 offset:51712
	ds_read_b128 v[180:183], v75 offset:6144
	ds_read_b128 v[176:179], v75 offset:6656
	v_mfma_f32_32x32x16_bf16 v[48:63], v[164:167], v[128:131], v[48:63]
	v_exp_f32_e32 v106, v106
	v_exp_f32_e32 v107, v107
	ds_read_b64_tr_b16 v[128:129], v209 offset:55296
	ds_read_b64_tr_b16 v[130:131], v209 offset:55808
	v_mfma_f32_32x32x16_bf16 v[32:47], v[160:163], v[112:115], v[32:47]
	v_exp_f32_e32 v108, v108
	v_exp_f32_e32 v109, v109
	ds_read_b64_tr_b16 v[112:113], v209 offset:52224
	ds_read_b64_tr_b16 v[114:115], v209 offset:52736
	v_mfma_f32_32x32x16_bf16 v[48:63], v[160:163], v[70:73], v[48:63]
	v_exp_f32_e32 v110, v110
	v_exp_f32_e32 v111, v111
	ds_read_b64_tr_b16 v[70:71], v209 offset:56320
	ds_read_b64_tr_b16 v[72:73], v209 offset:56832
	s_waitcnt lgkmcnt(14)
	v_mfma_f32_32x32x16_bf16 v[0:15], v[172:175], v[66:69], v[0:15]
	v_exp_f32_e32 v80, v80
	v_exp_f32_e32 v81, v81
	v_mfma_f32_32x32x16_bf16 v[16:31], v[172:175], v[76:79], v[16:31]
	v_exp_f32_e32 v82, v82
	v_exp_f32_e32 v83, v83
	v_mfma_f32_32x32x16_bf16 v[0:15], v[168:171], v[116:119], v[0:15]
	v_exp_f32_e32 v84, v84
	v_exp_f32_e32 v85, v85
	s_waitcnt lgkmcnt(12)
	v_mfma_f32_32x32x16_bf16 v[16:31], v[168:171], v[120:123], v[16:31]
	v_exp_f32_e32 v86, v86
	v_exp_f32_e32 v87, v87
	s_waitcnt lgkmcnt(8)
	v_mfma_f32_32x32x16_bf16 v[0:15], v[164:167], v[124:127], v[0:15]
	v_exp_f32_e32 v88, v88
	v_exp_f32_e32 v89, v89
	s_waitcnt lgkmcnt(4)
	v_mfma_f32_32x32x16_bf16 v[16:31], v[164:167], v[128:131], v[16:31]
	v_exp_f32_e32 v90, v90
	v_exp_f32_e32 v91, v91
	s_waitcnt lgkmcnt(2)
	v_mfma_f32_32x32x16_bf16 v[0:15], v[160:163], v[112:115], v[0:15]
	v_exp_f32_e32 v92, v92
	v_exp_f32_e32 v93, v93
	s_waitcnt lgkmcnt(0)
	v_mfma_f32_32x32x16_bf16 v[16:31], v[160:163], v[70:73], v[16:31]
	v_exp_f32_e32 v94, v94
	v_exp_f32_e32 v95, v95
	s_add_i32 s1, s42, 0x2000
	s_waitcnt vmcnt(3) lgkmcnt(0)
	s_barrier
; #define WAIT_BAR(N) asm volatile("s_waitcnt vmcnt(" #N ") lgkmcnt(0)\n\ts_barrier":::"memory")
;   #define RESC() do{ if(resc){ asm volatile("s_waitcnt lgkmcnt(0)":::"memory"); \
;       _Pragma("unroll") for(int d_=0;d_<2;++d_) _Pragma("unroll") for(int r=0;r<16;++r){const float f_=wsf[crow(r,hi)];o[d_][r]*=f_;o2[d_][r]*=f_;} } }while(0)
;   #define ROT() do{sl_prev=sl_cur;sl_cur=sl_next;sl_next=(sl_next==(NSLOT-1)*SLOTB)?0:sl_next+SLOTB;}while(0)
;   #define ENDW(tt) do{ if((tt)+3<NT){WAIT_BAR(3);} else if((tt)+2<NT){WAIT_BAR(2);} else {WAIT_BAR(0);} }while(0)
; template<int THRL> __device__ __forceinline__ void attn_unit(int b,int h,int qb,unsigned char*wsb,char*shm,float kmax,const int CMB,float lam){
;     ...
;   for(;t+5<NT;t+=2){
;     STEP(pB0,pB1,pA0,pA1,t,true,true,true);     WAIT_BAR(3); RESC(); ROT();
;     STEP(pA0,pA1,pB0,pB1,t+1,true,true,true);   WAIT_BAR(3); RESC(); ROT();
;   }
;     ...
;   for(;t+1<NT;t+=2){
;     STEP(pB0,pB1,pA0,pA1,t,(t+3<NT),(t+1<NT),(t+1<NT));       ENDW(t);   RESC(); ROT();
;     STEP(pA0,pA1,pB0,pB1,t+1,(t+4<NT),(t+2<NT),(t+2<NT));     ENDW(t+1); RESC(); ROT();
;   }
	s_cmpk_lg_i32 s42, 0x4000
	v_add_f32_e32 v64, v64, v65
	s_mov_b32 s5, s36
	s_cselect_b32 s36, s1, 0
	s_add_i32 s33, s33, 2
	v_lshl_add_u64 v[210:211], v[210:211], 0, s[22:23]
	v_lshl_add_u64 v[212:213], v[212:213], 0, s[22:23]
	s_cmp_ge_u32 s33, s89
	v_add_f32_e32 v64, v64, v74
	s_cbranch_scc0 .LBB0_311
	ds_read_b32 v230, v246
	ds_read_b32 v231, v246 offset:2048
	ds_read_b32 v232, v246 offset:4096
	ds_read_b32 v233, v246 offset:6144
	ds_read_b32 v234, v246 offset:8192
	ds_read_b32 v235, v246 offset:10240
	ds_read_b32 v236, v246 offset:12288
	ds_read_b32 v237, v246 offset:14336
	ds_read_b32 v238, v246 offset:16384
	ds_read_b32 v239, v246 offset:18432
	ds_read_b32 v240, v246 offset:20480
	ds_read_b32 v241, v246 offset:22528
	ds_read_b32 v242, v246 offset:24576
	ds_read_b32 v243, v246 offset:26624
	ds_read_b32 v244, v246 offset:28672
	ds_read_b32 v245, v246 offset:30720
	ds_read_b32 v246, v246 offset:32768
	s_waitcnt lgkmcnt(0)
	s_nop 0
	s_nop 0
	s_nop 0
	s_nop 0
	s_add_i32 s6, s4, -3
	s_branch .LBB0_314
